# softmax cross-group reductions: first level fused into a DPP operand, each level's result produced in two registers so the lane swaps need no copy
# speedup vs baseline: 1.0145x; 1.0145x over previous
; #define LDS_WAIT() asm volatile("s_waitcnt lgkmcnt(0)" ::: "memory")
; __device__ __forceinline__ void attn_query8(const unsigned char* __restrict__ KV8, const bf16_t* __restrict__ Z, const int* __restrict__ SEL, bf16_t* __restrict__ YMIX, int t, LAS float* sbuf  ) {
;     ...
;     for (int h = 0; h < 8; ++h) {
;         float sv[4]; float mx = -__builtin_inff();
; #pragma unroll
;         for (int jj = 0; jj < 4; ++jj) { const int j = lane + 64 * jj; const float s = sbuf[h * 256 + j]; sv[jj] = (j < nsel) ? s : -__builtin_inff(); mx = fmaxf(mx, sv[jj]); }
;         mx = wave_max(mx); float sm = 0.f;
; #pragma unroll
;         for (int jj = 0; jj < 4; ++jj) { const int j = lane + 64 * jj; sv[jj] = (j < nsel) ? __expf(sv[jj] - mx) : 0.f; sm += sv[jj]; }
;         sm = wave_sum(sm); const float inv = 1.f / sm;
; #pragma unroll
;         for (int jj = 0; jj < 4; ++jj) sbuf[h * 256 + lane + 64 * jj] = sv[jj] * inv;
;     }
;     LDS_WAIT();
;     f32x2v o[8];
; #pragma unroll
;     for (int i = 0; i < 8; ++i) o[i] = (f32x2v){0.f, 0.f};
; #pragma unroll 1
;     for (int b = 0; b < nb; b += 3) {
;         kv8_issue(C, rs, lvo, 1024, iv, CLAMPB(b + 2));
;         kv8_pv(A, o, srow, b);
.Latt_nomask:
	v_max3_f32 v134, v150, v151, v152
	v_max3_f32 v134, v134, v153, v154
	v_max3_f32 v134, v134, v155, v156
	v_max3_f32 v134, v134, v157, v158
	v_max3_f32 v134, v134, v159, v160
	v_max3_f32 v134, v134, v161, v162
	v_max3_f32 v134, v134, v163, v164
	v_max3_f32 v134, v134, v165, v166
	v_max3_f32 v134, v134, v167, v168
	v_max3_f32 v134, v134, v169, v170
	v_max3_f32 v134, v134, v171, v172
	v_max3_f32 v134, v134, v173, v174
	v_max3_f32 v134, v134, v175, v176
	v_max3_f32 v134, v134, v177, v178
	v_max3_f32 v134, v134, v179, v180
	v_max_f32_e32 v134, v134, v181
	s_nop 1
	v_max_f32_dpp v135, v134, v134 row_ror:8 row_mask:0xf bank_mask:0xf
	v_max_f32_dpp v134, v134, v134 row_ror:8 row_mask:0xf bank_mask:0xf
	s_nop 1
	v_permlane16_swap_b32_e32 v134, v135
	v_max_f32_e32 v136, v134, v135
	v_max_f32_e32 v134, v134, v135
	s_nop 1
	v_permlane32_swap_b32_e32 v134, v136
	v_max_f32_e32 v134, v134, v136
	v_mul_f32_e32 v134, 0xbfb8aa3b, v134
	v_fma_f32 v150, v150, s28, v134
	v_fma_f32 v151, v151, s28, v134
	v_fma_f32 v152, v152, s28, v134
	v_fma_f32 v153, v153, s28, v134
	v_fma_f32 v154, v154, s28, v134
	v_fma_f32 v155, v155, s28, v134
	v_fma_f32 v156, v156, s28, v134
	v_fma_f32 v157, v157, s28, v134
	v_fma_f32 v158, v158, s28, v134
	v_fma_f32 v159, v159, s28, v134
	v_fma_f32 v160, v160, s28, v134
	v_fma_f32 v161, v161, s28, v134
	v_fma_f32 v162, v162, s28, v134
	v_fma_f32 v163, v163, s28, v134
	v_fma_f32 v164, v164, s28, v134
	v_fma_f32 v165, v165, s28, v134
	v_fma_f32 v166, v166, s28, v134
	v_fma_f32 v167, v167, s28, v134
	v_fma_f32 v168, v168, s28, v134
	v_fma_f32 v169, v169, s28, v134
	v_fma_f32 v170, v170, s28, v134
	v_fma_f32 v171, v171, s28, v134
	v_fma_f32 v172, v172, s28, v134
	v_fma_f32 v173, v173, s28, v134
	v_fma_f32 v174, v174, s28, v134
	v_fma_f32 v175, v175, s28, v134
	v_fma_f32 v176, v176, s28, v134
	v_fma_f32 v177, v177, s28, v134
	v_fma_f32 v178, v178, s28, v134
	v_fma_f32 v179, v179, s28, v134
	v_fma_f32 v180, v180, s28, v134
	v_fma_f32 v181, v181, s28, v134
	v_exp_f32_e32 v150, v150
	v_exp_f32_e32 v151, v151
	v_exp_f32_e32 v152, v152
	v_exp_f32_e32 v153, v153
	v_exp_f32_e32 v154, v154
	v_exp_f32_e32 v155, v155
	v_exp_f32_e32 v156, v156
	v_exp_f32_e32 v157, v157
	v_exp_f32_e32 v158, v158
	v_exp_f32_e32 v159, v159
	v_exp_f32_e32 v160, v160
	v_exp_f32_e32 v161, v161
	v_exp_f32_e32 v162, v162
	v_exp_f32_e32 v163, v163
	v_exp_f32_e32 v164, v164
	v_exp_f32_e32 v165, v165
	v_exp_f32_e32 v166, v166
	v_exp_f32_e32 v167, v167
	v_exp_f32_e32 v168, v168
	v_exp_f32_e32 v169, v169
	v_exp_f32_e32 v170, v170
	v_exp_f32_e32 v171, v171
	v_exp_f32_e32 v172, v172
	v_exp_f32_e32 v173, v173
	v_exp_f32_e32 v174, v174
	v_exp_f32_e32 v175, v175
	v_exp_f32_e32 v176, v176
	v_exp_f32_e32 v177, v177
	v_exp_f32_e32 v178, v178
	v_exp_f32_e32 v179, v179
	v_exp_f32_e32 v180, v180
	v_exp_f32_e32 v181, v181
	s_nop 0
	v_add_f32_e32 v134, v150, v151
	v_add_f32_e32 v134, v134, v152
	v_add_f32_e32 v134, v134, v153
	v_add_f32_e32 v134, v134, v154
	v_add_f32_e32 v134, v134, v155
	v_add_f32_e32 v134, v134, v156
	v_add_f32_e32 v134, v134, v157
	v_add_f32_e32 v134, v134, v158
	v_add_f32_e32 v134, v134, v159
	v_add_f32_e32 v134, v134, v160
	v_add_f32_e32 v134, v134, v161
	v_add_f32_e32 v134, v134, v162
	v_add_f32_e32 v134, v134, v163
	v_add_f32_e32 v134, v134, v164
	v_add_f32_e32 v134, v134, v165
	v_add_f32_e32 v134, v134, v166
	v_add_f32_e32 v134, v134, v167
	v_add_f32_e32 v134, v134, v168
	v_add_f32_e32 v134, v134, v169
	v_add_f32_e32 v134, v134, v170
	v_add_f32_e32 v134, v134, v171
	v_add_f32_e32 v134, v134, v172
	v_add_f32_e32 v134, v134, v173
	v_add_f32_e32 v134, v134, v174
	v_add_f32_e32 v134, v134, v175
	v_add_f32_e32 v134, v134, v176
	v_add_f32_e32 v134, v134, v177
	v_add_f32_e32 v134, v134, v178
	v_add_f32_e32 v134, v134, v179
	v_add_f32_e32 v134, v134, v180
	v_add_f32_e32 v134, v134, v181
	s_nop 1
	v_add_f32_dpp v135, v134, v134 row_ror:8 row_mask:0xf bank_mask:0xf
	v_add_f32_dpp v134, v134, v134 row_ror:8 row_mask:0xf bank_mask:0xf
	s_nop 1
	v_permlane16_swap_b32_e32 v134, v135
	v_add_f32_e32 v136, v134, v135
	v_add_f32_e32 v134, v134, v135
	s_nop 1
	v_permlane32_swap_b32_e32 v134, v136
	v_add_f32_e32 v134, v134, v136
	v_div_scale_f32 v132, s[8:9], v134, v134, 1.0
	v_rcp_f32_e32 v135, v132
	v_div_scale_f32 v133, vcc, 1.0, v134, 1.0
	v_fma_f32 v136, -v132, v135, 1.0
	v_fmac_f32_e32 v135, v136, v135
	v_mul_f32_e32 v136, v133, v135
	v_fma_f32 v137, -v132, v136, v133
	v_fmac_f32_e32 v136, v137, v135
	v_fma_f32 v132, -v132, v136, v133
	s_nop 1
	v_div_fmas_f32 v132, v132, v135, v136
	v_div_fixup_f32 v134, v132, v134, 1.0
	v_mov_b32_e32 v149, v134
	s_waitcnt vmcnt(31)
	ds_write_b32 v148, v240 offset:0
	ds_write_b32 v148, v241 offset:32
	ds_write_b32 v148, v242 offset:64
	ds_write_b32 v148, v243 offset:96
	v_cvt_pk_f32_fp8_e32 v[214:215], v0
	v_cvt_pk_f32_fp8_sdwa v[216:217], v0 src0_sel:WORD_1
	v_pk_mul_f32 v[198:199], v[150:151], v[214:215] op_sel_hi:[0,1]
	v_pk_mul_f32 v[200:201], v[150:151], v[216:217] op_sel_hi:[0,1]
	v_cvt_pk_f32_fp8_e32 v[218:219], v1
	v_cvt_pk_f32_fp8_sdwa v[220:221], v1 src0_sel:WORD_1
	v_pk_mul_f32 v[202:203], v[150:151], v[218:219] op_sel_hi:[0,1]
	v_pk_mul_f32 v[204:205], v[150:151], v[220:221] op_sel_hi:[0,1]
	v_cvt_pk_f32_fp8_e32 v[214:215], v2
	v_cvt_pk_f32_fp8_sdwa v[216:217], v2 src0_sel:WORD_1
	v_pk_mul_f32 v[206:207], v[150:151], v[214:215] op_sel_hi:[0,1]
	v_pk_mul_f32 v[208:209], v[150:151], v[216:217] op_sel_hi:[0,1]
	v_cvt_pk_f32_fp8_e32 v[218:219], v3
	v_cvt_pk_f32_fp8_sdwa v[220:221], v3 src0_sel:WORD_1
	v_pk_mul_f32 v[210:211], v[150:151], v[218:219] op_sel_hi:[0,1]
	v_pk_mul_f32 v[212:213], v[150:151], v[220:221] op_sel_hi:[0,1]
	s_waitcnt vmcnt(30)
; #define LAS __attribute__((address_space(3)))
; __device__ __forceinline__ void kv8_issue(u32x4 (&buf)[8], __amdgpu_buffer_rsrc_t rs, int voff  , int sbase  , const int (&iv)[4], int b) {
;     const int jj = b >> 3, l0 = (b & 7) * 8;
;     const int ivb = (jj == 0) ? iv[0] : (jj == 1) ? iv[1] : (jj == 2) ? iv[2] : iv[3];
; #pragma unroll
;     for (int u = 0; u < 8; ++u) { const int si = __builtin_amdgcn_readlane(ivb, l0 + u); buf[u] = __builtin_amdgcn_raw_buffer_load_b128(rs, voff, si * 2048 + sbase, KV8_AUX); }
; }
; __device__ __forceinline__ void kv8_pv(const u32x4 (&buf)[8], f32x2v (&o2)[8], const LAS float* srow, int b) {
;     const LAS f32x4* p4 = (const LAS f32x4*)(srow + b * 8);
;     const f32x4 p0 = p4[0], p1 = p4[1];
;     const float p[8] = {p0.x, p0.y, p0.z, p0.w, p1.x, p1.y, p1.z, p1.w};
; #pragma unroll
;     for (int u = 0; u < 8; ++u) {
;         const u32x4 v = buf[u]; const f32x2v pp = {p[u], p[u]};
;         o2[0] = __builtin_elementwise_fma(pp, __builtin_amdgcn_cvt_pk_f32_fp8(v.x, false), o2[0]); o2[1] = __builtin_elementwise_fma(pp, __builtin_amdgcn_cvt_pk_f32_fp8(v.x, true), o2[1]);
;         o2[2] = __builtin_elementwise_fma(pp, __builtin_amdgcn_cvt_pk_f32_fp8(v.y, false), o2[2]); o2[3] = __builtin_elementwise_fma(pp, __builtin_amdgcn_cvt_pk_f32_fp8(v.y, true), o2[3]);
;         o2[4] = __builtin_elementwise_fma(pp, __builtin_amdgcn_cvt_pk_f32_fp8(v.z, false), o2[4]); o2[5] = __builtin_elementwise_fma(pp, __builtin_amdgcn_cvt_pk_f32_fp8(v.z, true), o2[5]);
;         o2[6] = __builtin_elementwise_fma(pp, __builtin_amdgcn_cvt_pk_f32_fp8(v.w, false), o2[6]); o2[7] = __builtin_elementwise_fma(pp, __builtin_amdgcn_cvt_pk_f32_fp8(v.w, true), o2[7]);
;     }
	v_cvt_pk_f32_fp8_e32 v[214:215], v4
	v_cvt_pk_f32_fp8_sdwa v[216:217], v4 src0_sel:WORD_1
	v_pk_fma_f32 v[198:199], v[150:151], v[214:215], v[198:199] op_sel:[1,0,0]
	v_pk_fma_f32 v[200:201], v[150:151], v[216:217], v[200:201] op_sel:[1,0,0]
	v_cvt_pk_f32_fp8_e32 v[218:219], v5
	v_cvt_pk_f32_fp8_sdwa v[220:221], v5 src0_sel:WORD_1
	v_pk_fma_f32 v[202:203], v[150:151], v[218:219], v[202:203] op_sel:[1,0,0]
	v_pk_fma_f32 v[204:205], v[150:151], v[220:221], v[204:205] op_sel:[1,0,0]
	v_cvt_pk_f32_fp8_e32 v[214:215], v6
	v_cvt_pk_f32_fp8_sdwa v[216:217], v6 src0_sel:WORD_1
	v_pk_fma_f32 v[206:207], v[150:151], v[214:215], v[206:207] op_sel:[1,0,0]
	v_pk_fma_f32 v[208:209], v[150:151], v[216:217], v[208:209] op_sel:[1,0,0]
	v_cvt_pk_f32_fp8_e32 v[218:219], v7
	v_cvt_pk_f32_fp8_sdwa v[220:221], v7 src0_sel:WORD_1
	v_pk_fma_f32 v[210:211], v[150:151], v[218:219], v[210:211] op_sel:[1,0,0]
	v_pk_fma_f32 v[212:213], v[150:151], v[220:221], v[212:213] op_sel:[1,0,0]
	s_waitcnt vmcnt(29)
	v_cvt_pk_f32_fp8_e32 v[214:215], v8
	v_cvt_pk_f32_fp8_sdwa v[216:217], v8 src0_sel:WORD_1
	v_pk_fma_f32 v[198:199], v[152:153], v[214:215], v[198:199] op_sel_hi:[0,1,1]
	v_pk_fma_f32 v[200:201], v[152:153], v[216:217], v[200:201] op_sel_hi:[0,1,1]
	v_cvt_pk_f32_fp8_e32 v[218:219], v9
	v_cvt_pk_f32_fp8_sdwa v[220:221], v9 src0_sel:WORD_1
	v_pk_fma_f32 v[202:203], v[152:153], v[218:219], v[202:203] op_sel_hi:[0,1,1]
	v_pk_fma_f32 v[204:205], v[152:153], v[220:221], v[204:205] op_sel_hi:[0,1,1]
	v_cvt_pk_f32_fp8_e32 v[214:215], v10
	v_cvt_pk_f32_fp8_sdwa v[216:217], v10 src0_sel:WORD_1
	v_pk_fma_f32 v[206:207], v[152:153], v[214:215], v[206:207] op_sel_hi:[0,1,1]
	v_pk_fma_f32 v[208:209], v[152:153], v[216:217], v[208:209] op_sel_hi:[0,1,1]
	v_cvt_pk_f32_fp8_e32 v[218:219], v11
	v_cvt_pk_f32_fp8_sdwa v[220:221], v11 src0_sel:WORD_1
	v_pk_fma_f32 v[210:211], v[152:153], v[218:219], v[210:211] op_sel_hi:[0,1,1]
	v_pk_fma_f32 v[212:213], v[152:153], v[220:221], v[212:213] op_sel_hi:[0,1,1]
	s_waitcnt vmcnt(28)
	v_cvt_pk_f32_fp8_e32 v[214:215], v12
	v_cvt_pk_f32_fp8_sdwa v[216:217], v12 src0_sel:WORD_1
	v_pk_fma_f32 v[198:199], v[152:153], v[214:215], v[198:199] op_sel:[1,0,0]
	v_pk_fma_f32 v[200:201], v[152:153], v[216:217], v[200:201] op_sel:[1,0,0]
	v_cvt_pk_f32_fp8_e32 v[218:219], v13
	v_cvt_pk_f32_fp8_sdwa v[220:221], v13 src0_sel:WORD_1
	v_pk_fma_f32 v[202:203], v[152:153], v[218:219], v[202:203] op_sel:[1,0,0]
	v_pk_fma_f32 v[204:205], v[152:153], v[220:221], v[204:205] op_sel:[1,0,0]
	v_cvt_pk_f32_fp8_e32 v[214:215], v14
	v_cvt_pk_f32_fp8_sdwa v[216:217], v14 src0_sel:WORD_1
	v_pk_fma_f32 v[206:207], v[152:153], v[214:215], v[206:207] op_sel:[1,0,0]
	v_pk_fma_f32 v[208:209], v[152:153], v[216:217], v[208:209] op_sel:[1,0,0]
	v_cvt_pk_f32_fp8_e32 v[218:219], v15
	v_cvt_pk_f32_fp8_sdwa v[220:221], v15 src0_sel:WORD_1
	v_pk_fma_f32 v[210:211], v[152:153], v[218:219], v[210:211] op_sel:[1,0,0]
	v_pk_fma_f32 v[212:213], v[152:153], v[220:221], v[212:213] op_sel:[1,0,0]
	ds_read_b128 v[150:153], v139 offset:0
	s_waitcnt vmcnt(27)
	v_cvt_pk_f32_fp8_e32 v[214:215], v16
	v_cvt_pk_f32_fp8_sdwa v[216:217], v16 src0_sel:WORD_1
	v_pk_fma_f32 v[198:199], v[154:155], v[214:215], v[198:199] op_sel_hi:[0,1,1]
	v_pk_fma_f32 v[200:201], v[154:155], v[216:217], v[200:201] op_sel_hi:[0,1,1]
	v_cvt_pk_f32_fp8_e32 v[218:219], v17
	v_cvt_pk_f32_fp8_sdwa v[220:221], v17 src0_sel:WORD_1
	v_pk_fma_f32 v[202:203], v[154:155], v[218:219], v[202:203] op_sel_hi:[0,1,1]
	v_pk_fma_f32 v[204:205], v[154:155], v[220:221], v[204:205] op_sel_hi:[0,1,1]
	v_cvt_pk_f32_fp8_e32 v[214:215], v18
	v_cvt_pk_f32_fp8_sdwa v[216:217], v18 src0_sel:WORD_1
	v_pk_fma_f32 v[206:207], v[154:155], v[214:215], v[206:207] op_sel_hi:[0,1,1]
	v_pk_fma_f32 v[208:209], v[154:155], v[216:217], v[208:209] op_sel_hi:[0,1,1]
	v_cvt_pk_f32_fp8_e32 v[218:219], v19
	v_cvt_pk_f32_fp8_sdwa v[220:221], v19 src0_sel:WORD_1
	v_pk_fma_f32 v[210:211], v[154:155], v[218:219], v[210:211] op_sel_hi:[0,1,1]
	v_pk_fma_f32 v[212:213], v[154:155], v[220:221], v[212:213] op_sel_hi:[0,1,1]
	s_waitcnt vmcnt(26)
	v_cvt_pk_f32_fp8_e32 v[214:215], v20
	v_cvt_pk_f32_fp8_sdwa v[216:217], v20 src0_sel:WORD_1
	v_pk_fma_f32 v[198:199], v[154:155], v[214:215], v[198:199] op_sel:[1,0,0]
	v_pk_fma_f32 v[200:201], v[154:155], v[216:217], v[200:201] op_sel:[1,0,0]
	v_cvt_pk_f32_fp8_e32 v[218:219], v21
	v_cvt_pk_f32_fp8_sdwa v[220:221], v21 src0_sel:WORD_1
	v_pk_fma_f32 v[202:203], v[154:155], v[218:219], v[202:203] op_sel:[1,0,0]
	v_pk_fma_f32 v[204:205], v[154:155], v[220:221], v[204:205] op_sel:[1,0,0]
	v_cvt_pk_f32_fp8_e32 v[214:215], v22
	v_cvt_pk_f32_fp8_sdwa v[216:217], v22 src0_sel:WORD_1
	v_pk_fma_f32 v[206:207], v[154:155], v[214:215], v[206:207] op_sel:[1,0,0]
	v_pk_fma_f32 v[208:209], v[154:155], v[216:217], v[208:209] op_sel:[1,0,0]
	v_cvt_pk_f32_fp8_e32 v[218:219], v23
	v_cvt_pk_f32_fp8_sdwa v[220:221], v23 src0_sel:WORD_1
	v_pk_fma_f32 v[210:211], v[154:155], v[218:219], v[210:211] op_sel:[1,0,0]
	v_pk_fma_f32 v[212:213], v[154:155], v[220:221], v[212:213] op_sel:[1,0,0]
	s_waitcnt lgkmcnt(0)
	v_lshl_add_u32 v150, v150, 8, v138
	v_lshl_add_u32 v151, v151, 8, v138
	v_lshl_add_u32 v152, v152, 8, v138
	v_lshl_add_u32 v153, v153, 8, v138
	buffer_load_dwordx4 v[0:3], v150, s[16:19], s26 offen
	buffer_load_dwordx4 v[4:7], v151, s[16:19], s26 offen
	buffer_load_dwordx4 v[8:11], v152, s[16:19], s26 offen
	buffer_load_dwordx4 v[12:15], v153, s[16:19], s26 offen
	s_waitcnt vmcnt(29)
; #define LAS __attribute__((address_space(3)))
; __device__ __forceinline__ void kv8_issue(u32x4 (&buf)[8], __amdgpu_buffer_rsrc_t rs, int voff  , int sbase  , const int (&iv)[4], int b) {
;     const int jj = b >> 3, l0 = (b & 7) * 8;
;     const int ivb = (jj == 0) ? iv[0] : (jj == 1) ? iv[1] : (jj == 2) ? iv[2] : iv[3];
; #pragma unroll
;     for (int u = 0; u < 8; ++u) { const int si = __builtin_amdgcn_readlane(ivb, l0 + u); buf[u] = __builtin_amdgcn_raw_buffer_load_b128(rs, voff, si * 2048 + sbase, KV8_AUX); }
; }
; __device__ __forceinline__ void kv8_pv(const u32x4 (&buf)[8], f32x2v (&o2)[8], const LAS float* srow, int b) {
;     const LAS f32x4* p4 = (const LAS f32x4*)(srow + b * 8);
;     const f32x4 p0 = p4[0], p1 = p4[1];
;     const float p[8] = {p0.x, p0.y, p0.z, p0.w, p1.x, p1.y, p1.z, p1.w};
; #pragma unroll
;     for (int u = 0; u < 8; ++u) {
;         const u32x4 v = buf[u]; const f32x2v pp = {p[u], p[u]};
;         o2[0] = __builtin_elementwise_fma(pp, __builtin_amdgcn_cvt_pk_f32_fp8(v.x, false), o2[0]); o2[1] = __builtin_elementwise_fma(pp, __builtin_amdgcn_cvt_pk_f32_fp8(v.x, true), o2[1]);
;         o2[2] = __builtin_elementwise_fma(pp, __builtin_amdgcn_cvt_pk_f32_fp8(v.y, false), o2[2]); o2[3] = __builtin_elementwise_fma(pp, __builtin_amdgcn_cvt_pk_f32_fp8(v.y, true), o2[3]);
;         o2[4] = __builtin_elementwise_fma(pp, __builtin_amdgcn_cvt_pk_f32_fp8(v.z, false), o2[4]); o2[5] = __builtin_elementwise_fma(pp, __builtin_amdgcn_cvt_pk_f32_fp8(v.z, true), o2[5]);
;         o2[6] = __builtin_elementwise_fma(pp, __builtin_amdgcn_cvt_pk_f32_fp8(v.w, false), o2[6]); o2[7] = __builtin_elementwise_fma(pp, __builtin_amdgcn_cvt_pk_f32_fp8(v.w, true), o2[7]);
;     }
	v_cvt_pk_f32_fp8_e32 v[214:215], v24
	v_cvt_pk_f32_fp8_sdwa v[216:217], v24 src0_sel:WORD_1
	v_pk_fma_f32 v[198:199], v[156:157], v[214:215], v[198:199] op_sel_hi:[0,1,1]
	v_pk_fma_f32 v[200:201], v[156:157], v[216:217], v[200:201] op_sel_hi:[0,1,1]
	v_cvt_pk_f32_fp8_e32 v[218:219], v25
	v_cvt_pk_f32_fp8_sdwa v[220:221], v25 src0_sel:WORD_1
	v_pk_fma_f32 v[202:203], v[156:157], v[218:219], v[202:203] op_sel_hi:[0,1,1]
	v_pk_fma_f32 v[204:205], v[156:157], v[220:221], v[204:205] op_sel_hi:[0,1,1]
	v_cvt_pk_f32_fp8_e32 v[214:215], v26
	v_cvt_pk_f32_fp8_sdwa v[216:217], v26 src0_sel:WORD_1
	v_pk_fma_f32 v[206:207], v[156:157], v[214:215], v[206:207] op_sel_hi:[0,1,1]
	v_pk_fma_f32 v[208:209], v[156:157], v[216:217], v[208:209] op_sel_hi:[0,1,1]
	v_cvt_pk_f32_fp8_e32 v[218:219], v27
	v_cvt_pk_f32_fp8_sdwa v[220:221], v27 src0_sel:WORD_1
	v_pk_fma_f32 v[210:211], v[156:157], v[218:219], v[210:211] op_sel_hi:[0,1,1]
	v_pk_fma_f32 v[212:213], v[156:157], v[220:221], v[212:213] op_sel_hi:[0,1,1]
	s_waitcnt vmcnt(28)
	v_cvt_pk_f32_fp8_e32 v[214:215], v28
	v_cvt_pk_f32_fp8_sdwa v[216:217], v28 src0_sel:WORD_1
	v_pk_fma_f32 v[198:199], v[156:157], v[214:215], v[198:199] op_sel:[1,0,0]
	v_pk_fma_f32 v[200:201], v[156:157], v[216:217], v[200:201] op_sel:[1,0,0]
	v_cvt_pk_f32_fp8_e32 v[218:219], v29
	v_cvt_pk_f32_fp8_sdwa v[220:221], v29 src0_sel:WORD_1
	v_pk_fma_f32 v[202:203], v[156:157], v[218:219], v[202:203] op_sel:[1,0,0]
	v_pk_fma_f32 v[204:205], v[156:157], v[220:221], v[204:205] op_sel:[1,0,0]
	v_cvt_pk_f32_fp8_e32 v[214:215], v30
	v_cvt_pk_f32_fp8_sdwa v[216:217], v30 src0_sel:WORD_1
	v_pk_fma_f32 v[206:207], v[156:157], v[214:215], v[206:207] op_sel:[1,0,0]
	v_pk_fma_f32 v[208:209], v[156:157], v[216:217], v[208:209] op_sel:[1,0,0]
	v_cvt_pk_f32_fp8_e32 v[218:219], v31
	v_cvt_pk_f32_fp8_sdwa v[220:221], v31 src0_sel:WORD_1
	v_pk_fma_f32 v[210:211], v[156:157], v[218:219], v[210:211] op_sel:[1,0,0]
	v_pk_fma_f32 v[212:213], v[156:157], v[220:221], v[212:213] op_sel:[1,0,0]
	ds_read_b128 v[154:157], v139 offset:16
	s_waitcnt vmcnt(27)
	v_cvt_pk_f32_fp8_e32 v[214:215], v32
	v_cvt_pk_f32_fp8_sdwa v[216:217], v32 src0_sel:WORD_1
	v_pk_fma_f32 v[198:199], v[158:159], v[214:215], v[198:199] op_sel_hi:[0,1,1]
	v_pk_fma_f32 v[200:201], v[158:159], v[216:217], v[200:201] op_sel_hi:[0,1,1]
	v_cvt_pk_f32_fp8_e32 v[218:219], v33
	v_cvt_pk_f32_fp8_sdwa v[220:221], v33 src0_sel:WORD_1
	v_pk_fma_f32 v[202:203], v[158:159], v[218:219], v[202:203] op_sel_hi:[0,1,1]
	v_pk_fma_f32 v[204:205], v[158:159], v[220:221], v[204:205] op_sel_hi:[0,1,1]
	v_cvt_pk_f32_fp8_e32 v[214:215], v34
	v_cvt_pk_f32_fp8_sdwa v[216:217], v34 src0_sel:WORD_1
	v_pk_fma_f32 v[206:207], v[158:159], v[214:215], v[206:207] op_sel_hi:[0,1,1]
	v_pk_fma_f32 v[208:209], v[158:159], v[216:217], v[208:209] op_sel_hi:[0,1,1]
	v_cvt_pk_f32_fp8_e32 v[218:219], v35
	v_cvt_pk_f32_fp8_sdwa v[220:221], v35 src0_sel:WORD_1
	v_pk_fma_f32 v[210:211], v[158:159], v[218:219], v[210:211] op_sel_hi:[0,1,1]
	v_pk_fma_f32 v[212:213], v[158:159], v[220:221], v[212:213] op_sel_hi:[0,1,1]
	s_waitcnt vmcnt(26)
	v_cvt_pk_f32_fp8_e32 v[214:215], v36
	v_cvt_pk_f32_fp8_sdwa v[216:217], v36 src0_sel:WORD_1
	v_pk_fma_f32 v[198:199], v[158:159], v[214:215], v[198:199] op_sel:[1,0,0]
	v_pk_fma_f32 v[200:201], v[158:159], v[216:217], v[200:201] op_sel:[1,0,0]
	v_cvt_pk_f32_fp8_e32 v[218:219], v37
	v_cvt_pk_f32_fp8_sdwa v[220:221], v37 src0_sel:WORD_1
	v_pk_fma_f32 v[202:203], v[158:159], v[218:219], v[202:203] op_sel:[1,0,0]
	v_pk_fma_f32 v[204:205], v[158:159], v[220:221], v[204:205] op_sel:[1,0,0]
	v_cvt_pk_f32_fp8_e32 v[214:215], v38
	v_cvt_pk_f32_fp8_sdwa v[216:217], v38 src0_sel:WORD_1
	v_pk_fma_f32 v[206:207], v[158:159], v[214:215], v[206:207] op_sel:[1,0,0]
	v_pk_fma_f32 v[208:209], v[158:159], v[216:217], v[208:209] op_sel:[1,0,0]
	v_cvt_pk_f32_fp8_e32 v[218:219], v39
	v_cvt_pk_f32_fp8_sdwa v[220:221], v39 src0_sel:WORD_1
	v_pk_fma_f32 v[210:211], v[158:159], v[218:219], v[210:211] op_sel:[1,0,0]
	v_pk_fma_f32 v[212:213], v[158:159], v[220:221], v[212:213] op_sel:[1,0,0]
	s_waitcnt lgkmcnt(0)
	v_lshl_add_u32 v154, v154, 8, v138
	v_lshl_add_u32 v155, v155, 8, v138
	v_lshl_add_u32 v156, v156, 8, v138
	v_lshl_add_u32 v157, v157, 8, v138
	buffer_load_dwordx4 v[16:19], v154, s[16:19], s26 offen
	buffer_load_dwordx4 v[20:23], v155, s[16:19], s26 offen
	buffer_load_dwordx4 v[24:27], v156, s[16:19], s26 offen
	buffer_load_dwordx4 v[28:31], v157, s[16:19], s26 offen
	s_waitcnt vmcnt(29)
	v_cvt_pk_f32_fp8_e32 v[214:215], v40
	v_cvt_pk_f32_fp8_sdwa v[216:217], v40 src0_sel:WORD_1
	v_pk_fma_f32 v[198:199], v[160:161], v[214:215], v[198:199] op_sel_hi:[0,1,1]
	v_pk_fma_f32 v[200:201], v[160:161], v[216:217], v[200:201] op_sel_hi:[0,1,1]
	v_cvt_pk_f32_fp8_e32 v[218:219], v41
	v_cvt_pk_f32_fp8_sdwa v[220:221], v41 src0_sel:WORD_1
	v_pk_fma_f32 v[202:203], v[160:161], v[218:219], v[202:203] op_sel_hi:[0,1,1]
	v_pk_fma_f32 v[204:205], v[160:161], v[220:221], v[204:205] op_sel_hi:[0,1,1]
	v_cvt_pk_f32_fp8_e32 v[214:215], v42
	v_cvt_pk_f32_fp8_sdwa v[216:217], v42 src0_sel:WORD_1
	v_pk_fma_f32 v[206:207], v[160:161], v[214:215], v[206:207] op_sel_hi:[0,1,1]
	v_pk_fma_f32 v[208:209], v[160:161], v[216:217], v[208:209] op_sel_hi:[0,1,1]
	v_cvt_pk_f32_fp8_e32 v[218:219], v43
	v_cvt_pk_f32_fp8_sdwa v[220:221], v43 src0_sel:WORD_1
	v_pk_fma_f32 v[210:211], v[160:161], v[218:219], v[210:211] op_sel_hi:[0,1,1]
	v_pk_fma_f32 v[212:213], v[160:161], v[220:221], v[212:213] op_sel_hi:[0,1,1]
	s_waitcnt vmcnt(28)
; #define LAS __attribute__((address_space(3)))
; __device__ __forceinline__ void kv8_issue(u32x4 (&buf)[8], __amdgpu_buffer_rsrc_t rs, int voff  , int sbase  , const int (&iv)[4], int b) {
;     const int jj = b >> 3, l0 = (b & 7) * 8;
;     const int ivb = (jj == 0) ? iv[0] : (jj == 1) ? iv[1] : (jj == 2) ? iv[2] : iv[3];
; #pragma unroll
;     for (int u = 0; u < 8; ++u) { const int si = __builtin_amdgcn_readlane(ivb, l0 + u); buf[u] = __builtin_amdgcn_raw_buffer_load_b128(rs, voff, si * 2048 + sbase, KV8_AUX); }
; }
; __device__ __forceinline__ void kv8_pv(const u32x4 (&buf)[8], f32x2v (&o2)[8], const LAS float* srow, int b) {
;     const LAS f32x4* p4 = (const LAS f32x4*)(srow + b * 8);
;     const f32x4 p0 = p4[0], p1 = p4[1];
;     const float p[8] = {p0.x, p0.y, p0.z, p0.w, p1.x, p1.y, p1.z, p1.w};
; #pragma unroll
;     for (int u = 0; u < 8; ++u) {
;         const u32x4 v = buf[u]; const f32x2v pp = {p[u], p[u]};
;         o2[0] = __builtin_elementwise_fma(pp, __builtin_amdgcn_cvt_pk_f32_fp8(v.x, false), o2[0]); o2[1] = __builtin_elementwise_fma(pp, __builtin_amdgcn_cvt_pk_f32_fp8(v.x, true), o2[1]);
;         o2[2] = __builtin_elementwise_fma(pp, __builtin_amdgcn_cvt_pk_f32_fp8(v.y, false), o2[2]); o2[3] = __builtin_elementwise_fma(pp, __builtin_amdgcn_cvt_pk_f32_fp8(v.y, true), o2[3]);
;         o2[4] = __builtin_elementwise_fma(pp, __builtin_amdgcn_cvt_pk_f32_fp8(v.z, false), o2[4]); o2[5] = __builtin_elementwise_fma(pp, __builtin_amdgcn_cvt_pk_f32_fp8(v.z, true), o2[5]);
;         o2[6] = __builtin_elementwise_fma(pp, __builtin_amdgcn_cvt_pk_f32_fp8(v.w, false), o2[6]); o2[7] = __builtin_elementwise_fma(pp, __builtin_amdgcn_cvt_pk_f32_fp8(v.w, true), o2[7]);
;     }
	v_cvt_pk_f32_fp8_e32 v[214:215], v44
	v_cvt_pk_f32_fp8_sdwa v[216:217], v44 src0_sel:WORD_1
	v_pk_fma_f32 v[198:199], v[160:161], v[214:215], v[198:199] op_sel:[1,0,0]
	v_pk_fma_f32 v[200:201], v[160:161], v[216:217], v[200:201] op_sel:[1,0,0]
	v_cvt_pk_f32_fp8_e32 v[218:219], v45
	v_cvt_pk_f32_fp8_sdwa v[220:221], v45 src0_sel:WORD_1
	v_pk_fma_f32 v[202:203], v[160:161], v[218:219], v[202:203] op_sel:[1,0,0]
	v_pk_fma_f32 v[204:205], v[160:161], v[220:221], v[204:205] op_sel:[1,0,0]
	v_cvt_pk_f32_fp8_e32 v[214:215], v46
	v_cvt_pk_f32_fp8_sdwa v[216:217], v46 src0_sel:WORD_1
	v_pk_fma_f32 v[206:207], v[160:161], v[214:215], v[206:207] op_sel:[1,0,0]
	v_pk_fma_f32 v[208:209], v[160:161], v[216:217], v[208:209] op_sel:[1,0,0]
	v_cvt_pk_f32_fp8_e32 v[218:219], v47
	v_cvt_pk_f32_fp8_sdwa v[220:221], v47 src0_sel:WORD_1
	v_pk_fma_f32 v[210:211], v[160:161], v[218:219], v[210:211] op_sel:[1,0,0]
	v_pk_fma_f32 v[212:213], v[160:161], v[220:221], v[212:213] op_sel:[1,0,0]
	ds_read_b128 v[158:161], v139 offset:32
	s_waitcnt vmcnt(27)
	v_cvt_pk_f32_fp8_e32 v[214:215], v48
	v_cvt_pk_f32_fp8_sdwa v[216:217], v48 src0_sel:WORD_1
	v_pk_fma_f32 v[198:199], v[162:163], v[214:215], v[198:199] op_sel_hi:[0,1,1]
	v_pk_fma_f32 v[200:201], v[162:163], v[216:217], v[200:201] op_sel_hi:[0,1,1]
	v_cvt_pk_f32_fp8_e32 v[218:219], v49
	v_cvt_pk_f32_fp8_sdwa v[220:221], v49 src0_sel:WORD_1
	v_pk_fma_f32 v[202:203], v[162:163], v[218:219], v[202:203] op_sel_hi:[0,1,1]
	v_pk_fma_f32 v[204:205], v[162:163], v[220:221], v[204:205] op_sel_hi:[0,1,1]
	v_cvt_pk_f32_fp8_e32 v[214:215], v50
	v_cvt_pk_f32_fp8_sdwa v[216:217], v50 src0_sel:WORD_1
	v_pk_fma_f32 v[206:207], v[162:163], v[214:215], v[206:207] op_sel_hi:[0,1,1]
	v_pk_fma_f32 v[208:209], v[162:163], v[216:217], v[208:209] op_sel_hi:[0,1,1]
	v_cvt_pk_f32_fp8_e32 v[218:219], v51
	v_cvt_pk_f32_fp8_sdwa v[220:221], v51 src0_sel:WORD_1
	v_pk_fma_f32 v[210:211], v[162:163], v[218:219], v[210:211] op_sel_hi:[0,1,1]
	v_pk_fma_f32 v[212:213], v[162:163], v[220:221], v[212:213] op_sel_hi:[0,1,1]
	s_waitcnt vmcnt(26)
	v_cvt_pk_f32_fp8_e32 v[214:215], v52
	v_cvt_pk_f32_fp8_sdwa v[216:217], v52 src0_sel:WORD_1
	v_pk_fma_f32 v[198:199], v[162:163], v[214:215], v[198:199] op_sel:[1,0,0]
	v_pk_fma_f32 v[200:201], v[162:163], v[216:217], v[200:201] op_sel:[1,0,0]
	v_cvt_pk_f32_fp8_e32 v[218:219], v53
	v_cvt_pk_f32_fp8_sdwa v[220:221], v53 src0_sel:WORD_1
	v_pk_fma_f32 v[202:203], v[162:163], v[218:219], v[202:203] op_sel:[1,0,0]
	v_pk_fma_f32 v[204:205], v[162:163], v[220:221], v[204:205] op_sel:[1,0,0]
	v_cvt_pk_f32_fp8_e32 v[214:215], v54
	v_cvt_pk_f32_fp8_sdwa v[216:217], v54 src0_sel:WORD_1
	v_pk_fma_f32 v[206:207], v[162:163], v[214:215], v[206:207] op_sel:[1,0,0]
	v_pk_fma_f32 v[208:209], v[162:163], v[216:217], v[208:209] op_sel:[1,0,0]
	v_cvt_pk_f32_fp8_e32 v[218:219], v55
	v_cvt_pk_f32_fp8_sdwa v[220:221], v55 src0_sel:WORD_1
	v_pk_fma_f32 v[210:211], v[162:163], v[218:219], v[210:211] op_sel:[1,0,0]
	v_pk_fma_f32 v[212:213], v[162:163], v[220:221], v[212:213] op_sel:[1,0,0]
	s_waitcnt lgkmcnt(0)
	v_lshl_add_u32 v158, v158, 8, v138
	v_lshl_add_u32 v159, v159, 8, v138
	v_lshl_add_u32 v160, v160, 8, v138
	v_lshl_add_u32 v161, v161, 8, v138
	buffer_load_dwordx4 v[32:35], v158, s[16:19], s26 offen
	buffer_load_dwordx4 v[36:39], v159, s[16:19], s26 offen
	buffer_load_dwordx4 v[40:43], v160, s[16:19], s26 offen
	buffer_load_dwordx4 v[44:47], v161, s[16:19], s26 offen
	s_waitcnt vmcnt(29)
	v_cvt_pk_f32_fp8_e32 v[214:215], v56
	v_cvt_pk_f32_fp8_sdwa v[216:217], v56 src0_sel:WORD_1
	v_pk_fma_f32 v[198:199], v[164:165], v[214:215], v[198:199] op_sel_hi:[0,1,1]
	v_pk_fma_f32 v[200:201], v[164:165], v[216:217], v[200:201] op_sel_hi:[0,1,1]
	v_cvt_pk_f32_fp8_e32 v[218:219], v57
	v_cvt_pk_f32_fp8_sdwa v[220:221], v57 src0_sel:WORD_1
	v_pk_fma_f32 v[202:203], v[164:165], v[218:219], v[202:203] op_sel_hi:[0,1,1]
	v_pk_fma_f32 v[204:205], v[164:165], v[220:221], v[204:205] op_sel_hi:[0,1,1]
	v_cvt_pk_f32_fp8_e32 v[214:215], v58
	v_cvt_pk_f32_fp8_sdwa v[216:217], v58 src0_sel:WORD_1
	v_pk_fma_f32 v[206:207], v[164:165], v[214:215], v[206:207] op_sel_hi:[0,1,1]
	v_pk_fma_f32 v[208:209], v[164:165], v[216:217], v[208:209] op_sel_hi:[0,1,1]
	v_cvt_pk_f32_fp8_e32 v[218:219], v59
	v_cvt_pk_f32_fp8_sdwa v[220:221], v59 src0_sel:WORD_1
	v_pk_fma_f32 v[210:211], v[164:165], v[218:219], v[210:211] op_sel_hi:[0,1,1]
	v_pk_fma_f32 v[212:213], v[164:165], v[220:221], v[212:213] op_sel_hi:[0,1,1]
	s_waitcnt vmcnt(28)
	v_cvt_pk_f32_fp8_e32 v[214:215], v60
	v_cvt_pk_f32_fp8_sdwa v[216:217], v60 src0_sel:WORD_1
	v_pk_fma_f32 v[198:199], v[164:165], v[214:215], v[198:199] op_sel:[1,0,0]
	v_pk_fma_f32 v[200:201], v[164:165], v[216:217], v[200:201] op_sel:[1,0,0]
	v_cvt_pk_f32_fp8_e32 v[218:219], v61
	v_cvt_pk_f32_fp8_sdwa v[220:221], v61 src0_sel:WORD_1
	v_pk_fma_f32 v[202:203], v[164:165], v[218:219], v[202:203] op_sel:[1,0,0]
	v_pk_fma_f32 v[204:205], v[164:165], v[220:221], v[204:205] op_sel:[1,0,0]
	v_cvt_pk_f32_fp8_e32 v[214:215], v62
	v_cvt_pk_f32_fp8_sdwa v[216:217], v62 src0_sel:WORD_1
	v_pk_fma_f32 v[206:207], v[164:165], v[214:215], v[206:207] op_sel:[1,0,0]
	v_pk_fma_f32 v[208:209], v[164:165], v[216:217], v[208:209] op_sel:[1,0,0]
	v_cvt_pk_f32_fp8_e32 v[218:219], v63
	v_cvt_pk_f32_fp8_sdwa v[220:221], v63 src0_sel:WORD_1
	v_pk_fma_f32 v[210:211], v[164:165], v[218:219], v[210:211] op_sel:[1,0,0]
	v_pk_fma_f32 v[212:213], v[164:165], v[220:221], v[212:213] op_sel:[1,0,0]
	ds_read_b128 v[162:165], v139 offset:48
	s_waitcnt vmcnt(27)
; #define LAS __attribute__((address_space(3)))
; __device__ __forceinline__ void kv8_issue(u32x4 (&buf)[8], __amdgpu_buffer_rsrc_t rs, int voff  , int sbase  , const int (&iv)[4], int b) {
;     const int jj = b >> 3, l0 = (b & 7) * 8;
;     const int ivb = (jj == 0) ? iv[0] : (jj == 1) ? iv[1] : (jj == 2) ? iv[2] : iv[3];
; #pragma unroll
;     for (int u = 0; u < 8; ++u) { const int si = __builtin_amdgcn_readlane(ivb, l0 + u); buf[u] = __builtin_amdgcn_raw_buffer_load_b128(rs, voff, si * 2048 + sbase, KV8_AUX); }
; }
; __device__ __forceinline__ void kv8_pv(const u32x4 (&buf)[8], f32x2v (&o2)[8], const LAS float* srow, int b) {
;     const LAS f32x4* p4 = (const LAS f32x4*)(srow + b * 8);
;     const f32x4 p0 = p4[0], p1 = p4[1];
;     const float p[8] = {p0.x, p0.y, p0.z, p0.w, p1.x, p1.y, p1.z, p1.w};
; #pragma unroll
;     for (int u = 0; u < 8; ++u) {
;         const u32x4 v = buf[u]; const f32x2v pp = {p[u], p[u]};
;         o2[0] = __builtin_elementwise_fma(pp, __builtin_amdgcn_cvt_pk_f32_fp8(v.x, false), o2[0]); o2[1] = __builtin_elementwise_fma(pp, __builtin_amdgcn_cvt_pk_f32_fp8(v.x, true), o2[1]);
;         o2[2] = __builtin_elementwise_fma(pp, __builtin_amdgcn_cvt_pk_f32_fp8(v.y, false), o2[2]); o2[3] = __builtin_elementwise_fma(pp, __builtin_amdgcn_cvt_pk_f32_fp8(v.y, true), o2[3]);
;         o2[4] = __builtin_elementwise_fma(pp, __builtin_amdgcn_cvt_pk_f32_fp8(v.z, false), o2[4]); o2[5] = __builtin_elementwise_fma(pp, __builtin_amdgcn_cvt_pk_f32_fp8(v.z, true), o2[5]);
;         o2[6] = __builtin_elementwise_fma(pp, __builtin_amdgcn_cvt_pk_f32_fp8(v.w, false), o2[6]); o2[7] = __builtin_elementwise_fma(pp, __builtin_amdgcn_cvt_pk_f32_fp8(v.w, true), o2[7]);
;     }
	v_cvt_pk_f32_fp8_e32 v[214:215], v64
	v_cvt_pk_f32_fp8_sdwa v[216:217], v64 src0_sel:WORD_1
	v_pk_fma_f32 v[198:199], v[166:167], v[214:215], v[198:199] op_sel_hi:[0,1,1]
	v_pk_fma_f32 v[200:201], v[166:167], v[216:217], v[200:201] op_sel_hi:[0,1,1]
	v_cvt_pk_f32_fp8_e32 v[218:219], v65
	v_cvt_pk_f32_fp8_sdwa v[220:221], v65 src0_sel:WORD_1
	v_pk_fma_f32 v[202:203], v[166:167], v[218:219], v[202:203] op_sel_hi:[0,1,1]
	v_pk_fma_f32 v[204:205], v[166:167], v[220:221], v[204:205] op_sel_hi:[0,1,1]
	v_cvt_pk_f32_fp8_e32 v[214:215], v66
	v_cvt_pk_f32_fp8_sdwa v[216:217], v66 src0_sel:WORD_1
	v_pk_fma_f32 v[206:207], v[166:167], v[214:215], v[206:207] op_sel_hi:[0,1,1]
	v_pk_fma_f32 v[208:209], v[166:167], v[216:217], v[208:209] op_sel_hi:[0,1,1]
	v_cvt_pk_f32_fp8_e32 v[218:219], v67
	v_cvt_pk_f32_fp8_sdwa v[220:221], v67 src0_sel:WORD_1
	v_pk_fma_f32 v[210:211], v[166:167], v[218:219], v[210:211] op_sel_hi:[0,1,1]
	v_pk_fma_f32 v[212:213], v[166:167], v[220:221], v[212:213] op_sel_hi:[0,1,1]
	s_waitcnt vmcnt(26)
	v_cvt_pk_f32_fp8_e32 v[214:215], v68
	v_cvt_pk_f32_fp8_sdwa v[216:217], v68 src0_sel:WORD_1
	v_pk_fma_f32 v[198:199], v[166:167], v[214:215], v[198:199] op_sel:[1,0,0]
	v_pk_fma_f32 v[200:201], v[166:167], v[216:217], v[200:201] op_sel:[1,0,0]
	v_cvt_pk_f32_fp8_e32 v[218:219], v69
	v_cvt_pk_f32_fp8_sdwa v[220:221], v69 src0_sel:WORD_1
	v_pk_fma_f32 v[202:203], v[166:167], v[218:219], v[202:203] op_sel:[1,0,0]
	v_pk_fma_f32 v[204:205], v[166:167], v[220:221], v[204:205] op_sel:[1,0,0]
	v_cvt_pk_f32_fp8_e32 v[214:215], v70
	v_cvt_pk_f32_fp8_sdwa v[216:217], v70 src0_sel:WORD_1
	v_pk_fma_f32 v[206:207], v[166:167], v[214:215], v[206:207] op_sel:[1,0,0]
	v_pk_fma_f32 v[208:209], v[166:167], v[216:217], v[208:209] op_sel:[1,0,0]
	v_cvt_pk_f32_fp8_e32 v[218:219], v71
	v_cvt_pk_f32_fp8_sdwa v[220:221], v71 src0_sel:WORD_1
	v_pk_fma_f32 v[210:211], v[166:167], v[218:219], v[210:211] op_sel:[1,0,0]
	v_pk_fma_f32 v[212:213], v[166:167], v[220:221], v[212:213] op_sel:[1,0,0]
	s_waitcnt lgkmcnt(0)
	v_lshl_add_u32 v162, v162, 8, v138
	v_lshl_add_u32 v163, v163, 8, v138
	v_lshl_add_u32 v164, v164, 8, v138
	v_lshl_add_u32 v165, v165, 8, v138
	buffer_load_dwordx4 v[48:51], v162, s[16:19], s26 offen
	buffer_load_dwordx4 v[52:55], v163, s[16:19], s26 offen
	buffer_load_dwordx4 v[56:59], v164, s[16:19], s26 offen
	buffer_load_dwordx4 v[60:63], v165, s[16:19], s26 offen
	s_waitcnt vmcnt(29)
	v_cvt_pk_f32_fp8_e32 v[214:215], v72
	v_cvt_pk_f32_fp8_sdwa v[216:217], v72 src0_sel:WORD_1
	v_pk_fma_f32 v[198:199], v[168:169], v[214:215], v[198:199] op_sel_hi:[0,1,1]
	v_pk_fma_f32 v[200:201], v[168:169], v[216:217], v[200:201] op_sel_hi:[0,1,1]
	v_cvt_pk_f32_fp8_e32 v[218:219], v73
	v_cvt_pk_f32_fp8_sdwa v[220:221], v73 src0_sel:WORD_1
	v_pk_fma_f32 v[202:203], v[168:169], v[218:219], v[202:203] op_sel_hi:[0,1,1]
	v_pk_fma_f32 v[204:205], v[168:169], v[220:221], v[204:205] op_sel_hi:[0,1,1]
	v_cvt_pk_f32_fp8_e32 v[214:215], v74
	v_cvt_pk_f32_fp8_sdwa v[216:217], v74 src0_sel:WORD_1
	v_pk_fma_f32 v[206:207], v[168:169], v[214:215], v[206:207] op_sel_hi:[0,1,1]
	v_pk_fma_f32 v[208:209], v[168:169], v[216:217], v[208:209] op_sel_hi:[0,1,1]
	v_cvt_pk_f32_fp8_e32 v[218:219], v75
	v_cvt_pk_f32_fp8_sdwa v[220:221], v75 src0_sel:WORD_1
	v_pk_fma_f32 v[210:211], v[168:169], v[218:219], v[210:211] op_sel_hi:[0,1,1]
	v_pk_fma_f32 v[212:213], v[168:169], v[220:221], v[212:213] op_sel_hi:[0,1,1]
	s_waitcnt vmcnt(28)
	v_cvt_pk_f32_fp8_e32 v[214:215], v76
	v_cvt_pk_f32_fp8_sdwa v[216:217], v76 src0_sel:WORD_1
	v_pk_fma_f32 v[198:199], v[168:169], v[214:215], v[198:199] op_sel:[1,0,0]
	v_pk_fma_f32 v[200:201], v[168:169], v[216:217], v[200:201] op_sel:[1,0,0]
	v_cvt_pk_f32_fp8_e32 v[218:219], v77
	v_cvt_pk_f32_fp8_sdwa v[220:221], v77 src0_sel:WORD_1
	v_pk_fma_f32 v[202:203], v[168:169], v[218:219], v[202:203] op_sel:[1,0,0]
	v_pk_fma_f32 v[204:205], v[168:169], v[220:221], v[204:205] op_sel:[1,0,0]
	v_cvt_pk_f32_fp8_e32 v[214:215], v78
	v_cvt_pk_f32_fp8_sdwa v[216:217], v78 src0_sel:WORD_1
	v_pk_fma_f32 v[206:207], v[168:169], v[214:215], v[206:207] op_sel:[1,0,0]
	v_pk_fma_f32 v[208:209], v[168:169], v[216:217], v[208:209] op_sel:[1,0,0]
	v_cvt_pk_f32_fp8_e32 v[218:219], v79
	v_cvt_pk_f32_fp8_sdwa v[220:221], v79 src0_sel:WORD_1
	v_pk_fma_f32 v[210:211], v[168:169], v[218:219], v[210:211] op_sel:[1,0,0]
	v_pk_fma_f32 v[212:213], v[168:169], v[220:221], v[212:213] op_sel:[1,0,0]
	ds_read_b128 v[166:169], v139 offset:64
	s_waitcnt vmcnt(27)
	v_cvt_pk_f32_fp8_e32 v[214:215], v80
	v_cvt_pk_f32_fp8_sdwa v[216:217], v80 src0_sel:WORD_1
	v_pk_fma_f32 v[198:199], v[170:171], v[214:215], v[198:199] op_sel_hi:[0,1,1]
	v_pk_fma_f32 v[200:201], v[170:171], v[216:217], v[200:201] op_sel_hi:[0,1,1]
	v_cvt_pk_f32_fp8_e32 v[218:219], v81
	v_cvt_pk_f32_fp8_sdwa v[220:221], v81 src0_sel:WORD_1
	v_pk_fma_f32 v[202:203], v[170:171], v[218:219], v[202:203] op_sel_hi:[0,1,1]
	v_pk_fma_f32 v[204:205], v[170:171], v[220:221], v[204:205] op_sel_hi:[0,1,1]
	v_cvt_pk_f32_fp8_e32 v[214:215], v82
	v_cvt_pk_f32_fp8_sdwa v[216:217], v82 src0_sel:WORD_1
	v_pk_fma_f32 v[206:207], v[170:171], v[214:215], v[206:207] op_sel_hi:[0,1,1]
	v_pk_fma_f32 v[208:209], v[170:171], v[216:217], v[208:209] op_sel_hi:[0,1,1]
	v_cvt_pk_f32_fp8_e32 v[218:219], v83
	v_cvt_pk_f32_fp8_sdwa v[220:221], v83 src0_sel:WORD_1
	v_pk_fma_f32 v[210:211], v[170:171], v[218:219], v[210:211] op_sel_hi:[0,1,1]
	v_pk_fma_f32 v[212:213], v[170:171], v[220:221], v[212:213] op_sel_hi:[0,1,1]
	s_waitcnt vmcnt(26)
; #define LAS __attribute__((address_space(3)))
; __device__ __forceinline__ void kv8_issue(u32x4 (&buf)[8], __amdgpu_buffer_rsrc_t rs, int voff  , int sbase  , const int (&iv)[4], int b) {
;     const int jj = b >> 3, l0 = (b & 7) * 8;
;     const int ivb = (jj == 0) ? iv[0] : (jj == 1) ? iv[1] : (jj == 2) ? iv[2] : iv[3];
; #pragma unroll
;     for (int u = 0; u < 8; ++u) { const int si = __builtin_amdgcn_readlane(ivb, l0 + u); buf[u] = __builtin_amdgcn_raw_buffer_load_b128(rs, voff, si * 2048 + sbase, KV8_AUX); }
; }
; __device__ __forceinline__ void kv8_pv(const u32x4 (&buf)[8], f32x2v (&o2)[8], const LAS float* srow, int b) {
;     const LAS f32x4* p4 = (const LAS f32x4*)(srow + b * 8);
;     const f32x4 p0 = p4[0], p1 = p4[1];
;     const float p[8] = {p0.x, p0.y, p0.z, p0.w, p1.x, p1.y, p1.z, p1.w};
; #pragma unroll
;     for (int u = 0; u < 8; ++u) {
;         const u32x4 v = buf[u]; const f32x2v pp = {p[u], p[u]};
;         o2[0] = __builtin_elementwise_fma(pp, __builtin_amdgcn_cvt_pk_f32_fp8(v.x, false), o2[0]); o2[1] = __builtin_elementwise_fma(pp, __builtin_amdgcn_cvt_pk_f32_fp8(v.x, true), o2[1]);
;         o2[2] = __builtin_elementwise_fma(pp, __builtin_amdgcn_cvt_pk_f32_fp8(v.y, false), o2[2]); o2[3] = __builtin_elementwise_fma(pp, __builtin_amdgcn_cvt_pk_f32_fp8(v.y, true), o2[3]);
;         o2[4] = __builtin_elementwise_fma(pp, __builtin_amdgcn_cvt_pk_f32_fp8(v.z, false), o2[4]); o2[5] = __builtin_elementwise_fma(pp, __builtin_amdgcn_cvt_pk_f32_fp8(v.z, true), o2[5]);
;         o2[6] = __builtin_elementwise_fma(pp, __builtin_amdgcn_cvt_pk_f32_fp8(v.w, false), o2[6]); o2[7] = __builtin_elementwise_fma(pp, __builtin_amdgcn_cvt_pk_f32_fp8(v.w, true), o2[7]);
;     }
	v_cvt_pk_f32_fp8_e32 v[214:215], v84
	v_cvt_pk_f32_fp8_sdwa v[216:217], v84 src0_sel:WORD_1
	v_pk_fma_f32 v[198:199], v[170:171], v[214:215], v[198:199] op_sel:[1,0,0]
	v_pk_fma_f32 v[200:201], v[170:171], v[216:217], v[200:201] op_sel:[1,0,0]
	v_cvt_pk_f32_fp8_e32 v[218:219], v85
	v_cvt_pk_f32_fp8_sdwa v[220:221], v85 src0_sel:WORD_1
	v_pk_fma_f32 v[202:203], v[170:171], v[218:219], v[202:203] op_sel:[1,0,0]
	v_pk_fma_f32 v[204:205], v[170:171], v[220:221], v[204:205] op_sel:[1,0,0]
	v_cvt_pk_f32_fp8_e32 v[214:215], v86
	v_cvt_pk_f32_fp8_sdwa v[216:217], v86 src0_sel:WORD_1
	v_pk_fma_f32 v[206:207], v[170:171], v[214:215], v[206:207] op_sel:[1,0,0]
	v_pk_fma_f32 v[208:209], v[170:171], v[216:217], v[208:209] op_sel:[1,0,0]
	v_cvt_pk_f32_fp8_e32 v[218:219], v87
	v_cvt_pk_f32_fp8_sdwa v[220:221], v87 src0_sel:WORD_1
	v_pk_fma_f32 v[210:211], v[170:171], v[218:219], v[210:211] op_sel:[1,0,0]
	v_pk_fma_f32 v[212:213], v[170:171], v[220:221], v[212:213] op_sel:[1,0,0]
	s_waitcnt lgkmcnt(0)
	v_lshl_add_u32 v166, v166, 8, v138
	v_lshl_add_u32 v167, v167, 8, v138
	v_lshl_add_u32 v168, v168, 8, v138
	v_lshl_add_u32 v169, v169, 8, v138
	buffer_load_dwordx4 v[64:67], v166, s[16:19], s26 offen
	buffer_load_dwordx4 v[68:71], v167, s[16:19], s26 offen
	buffer_load_dwordx4 v[72:75], v168, s[16:19], s26 offen
	buffer_load_dwordx4 v[76:79], v169, s[16:19], s26 offen
	s_waitcnt vmcnt(29)
	v_cvt_pk_f32_fp8_e32 v[214:215], v88
	v_cvt_pk_f32_fp8_sdwa v[216:217], v88 src0_sel:WORD_1
	v_pk_fma_f32 v[198:199], v[172:173], v[214:215], v[198:199] op_sel_hi:[0,1,1]
	v_pk_fma_f32 v[200:201], v[172:173], v[216:217], v[200:201] op_sel_hi:[0,1,1]
	v_cvt_pk_f32_fp8_e32 v[218:219], v89
	v_cvt_pk_f32_fp8_sdwa v[220:221], v89 src0_sel:WORD_1
	v_pk_fma_f32 v[202:203], v[172:173], v[218:219], v[202:203] op_sel_hi:[0,1,1]
	v_pk_fma_f32 v[204:205], v[172:173], v[220:221], v[204:205] op_sel_hi:[0,1,1]
	v_cvt_pk_f32_fp8_e32 v[214:215], v90
	v_cvt_pk_f32_fp8_sdwa v[216:217], v90 src0_sel:WORD_1
	v_pk_fma_f32 v[206:207], v[172:173], v[214:215], v[206:207] op_sel_hi:[0,1,1]
	v_pk_fma_f32 v[208:209], v[172:173], v[216:217], v[208:209] op_sel_hi:[0,1,1]
	v_cvt_pk_f32_fp8_e32 v[218:219], v91
	v_cvt_pk_f32_fp8_sdwa v[220:221], v91 src0_sel:WORD_1
	v_pk_fma_f32 v[210:211], v[172:173], v[218:219], v[210:211] op_sel_hi:[0,1,1]
	v_pk_fma_f32 v[212:213], v[172:173], v[220:221], v[212:213] op_sel_hi:[0,1,1]
	s_waitcnt vmcnt(28)
	v_cvt_pk_f32_fp8_e32 v[214:215], v92
	v_cvt_pk_f32_fp8_sdwa v[216:217], v92 src0_sel:WORD_1
	v_pk_fma_f32 v[198:199], v[172:173], v[214:215], v[198:199] op_sel:[1,0,0]
	v_pk_fma_f32 v[200:201], v[172:173], v[216:217], v[200:201] op_sel:[1,0,0]
	v_cvt_pk_f32_fp8_e32 v[218:219], v93
	v_cvt_pk_f32_fp8_sdwa v[220:221], v93 src0_sel:WORD_1
	v_pk_fma_f32 v[202:203], v[172:173], v[218:219], v[202:203] op_sel:[1,0,0]
	v_pk_fma_f32 v[204:205], v[172:173], v[220:221], v[204:205] op_sel:[1,0,0]
	v_cvt_pk_f32_fp8_e32 v[214:215], v94
	v_cvt_pk_f32_fp8_sdwa v[216:217], v94 src0_sel:WORD_1
	v_pk_fma_f32 v[206:207], v[172:173], v[214:215], v[206:207] op_sel:[1,0,0]
	v_pk_fma_f32 v[208:209], v[172:173], v[216:217], v[208:209] op_sel:[1,0,0]
	v_cvt_pk_f32_fp8_e32 v[218:219], v95
	v_cvt_pk_f32_fp8_sdwa v[220:221], v95 src0_sel:WORD_1
	v_pk_fma_f32 v[210:211], v[172:173], v[218:219], v[210:211] op_sel:[1,0,0]
	v_pk_fma_f32 v[212:213], v[172:173], v[220:221], v[212:213] op_sel:[1,0,0]
	ds_read_b128 v[170:173], v139 offset:80
	s_waitcnt vmcnt(27)
	v_cvt_pk_f32_fp8_e32 v[214:215], v96
	v_cvt_pk_f32_fp8_sdwa v[216:217], v96 src0_sel:WORD_1
	v_pk_fma_f32 v[198:199], v[174:175], v[214:215], v[198:199] op_sel_hi:[0,1,1]
	v_pk_fma_f32 v[200:201], v[174:175], v[216:217], v[200:201] op_sel_hi:[0,1,1]
	v_cvt_pk_f32_fp8_e32 v[218:219], v97
	v_cvt_pk_f32_fp8_sdwa v[220:221], v97 src0_sel:WORD_1
	v_pk_fma_f32 v[202:203], v[174:175], v[218:219], v[202:203] op_sel_hi:[0,1,1]
	v_pk_fma_f32 v[204:205], v[174:175], v[220:221], v[204:205] op_sel_hi:[0,1,1]
	v_cvt_pk_f32_fp8_e32 v[214:215], v98
	v_cvt_pk_f32_fp8_sdwa v[216:217], v98 src0_sel:WORD_1
	v_pk_fma_f32 v[206:207], v[174:175], v[214:215], v[206:207] op_sel_hi:[0,1,1]
	v_pk_fma_f32 v[208:209], v[174:175], v[216:217], v[208:209] op_sel_hi:[0,1,1]
	v_cvt_pk_f32_fp8_e32 v[218:219], v99
	v_cvt_pk_f32_fp8_sdwa v[220:221], v99 src0_sel:WORD_1
	v_pk_fma_f32 v[210:211], v[174:175], v[218:219], v[210:211] op_sel_hi:[0,1,1]
	v_pk_fma_f32 v[212:213], v[174:175], v[220:221], v[212:213] op_sel_hi:[0,1,1]
	s_waitcnt vmcnt(26)
	v_cvt_pk_f32_fp8_e32 v[214:215], v100
	v_cvt_pk_f32_fp8_sdwa v[216:217], v100 src0_sel:WORD_1
	v_pk_fma_f32 v[198:199], v[174:175], v[214:215], v[198:199] op_sel:[1,0,0]
	v_pk_fma_f32 v[200:201], v[174:175], v[216:217], v[200:201] op_sel:[1,0,0]
	v_cvt_pk_f32_fp8_e32 v[218:219], v101
	v_cvt_pk_f32_fp8_sdwa v[220:221], v101 src0_sel:WORD_1
	v_pk_fma_f32 v[202:203], v[174:175], v[218:219], v[202:203] op_sel:[1,0,0]
	v_pk_fma_f32 v[204:205], v[174:175], v[220:221], v[204:205] op_sel:[1,0,0]
	v_cvt_pk_f32_fp8_e32 v[214:215], v102
	v_cvt_pk_f32_fp8_sdwa v[216:217], v102 src0_sel:WORD_1
	v_pk_fma_f32 v[206:207], v[174:175], v[214:215], v[206:207] op_sel:[1,0,0]
	v_pk_fma_f32 v[208:209], v[174:175], v[216:217], v[208:209] op_sel:[1,0,0]
	v_cvt_pk_f32_fp8_e32 v[218:219], v103
	v_cvt_pk_f32_fp8_sdwa v[220:221], v103 src0_sel:WORD_1
	v_pk_fma_f32 v[210:211], v[174:175], v[218:219], v[210:211] op_sel:[1,0,0]
	v_pk_fma_f32 v[212:213], v[174:175], v[220:221], v[212:213] op_sel:[1,0,0]
	s_waitcnt lgkmcnt(0)
; #define LAS __attribute__((address_space(3)))
; __device__ __forceinline__ void kv8_issue(u32x4 (&buf)[8], __amdgpu_buffer_rsrc_t rs, int voff  , int sbase  , const int (&iv)[4], int b) {
;     const int jj = b >> 3, l0 = (b & 7) * 8;
;     const int ivb = (jj == 0) ? iv[0] : (jj == 1) ? iv[1] : (jj == 2) ? iv[2] : iv[3];
; #pragma unroll
;     for (int u = 0; u < 8; ++u) { const int si = __builtin_amdgcn_readlane(ivb, l0 + u); buf[u] = __builtin_amdgcn_raw_buffer_load_b128(rs, voff, si * 2048 + sbase, KV8_AUX); }
; }
; __device__ __forceinline__ void kv8_pv(const u32x4 (&buf)[8], f32x2v (&o2)[8], const LAS float* srow, int b) {
;     const LAS f32x4* p4 = (const LAS f32x4*)(srow + b * 8);
;     const f32x4 p0 = p4[0], p1 = p4[1];
;     const float p[8] = {p0.x, p0.y, p0.z, p0.w, p1.x, p1.y, p1.z, p1.w};
; #pragma unroll
;     for (int u = 0; u < 8; ++u) {
;         const u32x4 v = buf[u]; const f32x2v pp = {p[u], p[u]};
;         o2[0] = __builtin_elementwise_fma(pp, __builtin_amdgcn_cvt_pk_f32_fp8(v.x, false), o2[0]); o2[1] = __builtin_elementwise_fma(pp, __builtin_amdgcn_cvt_pk_f32_fp8(v.x, true), o2[1]);
;         o2[2] = __builtin_elementwise_fma(pp, __builtin_amdgcn_cvt_pk_f32_fp8(v.y, false), o2[2]); o2[3] = __builtin_elementwise_fma(pp, __builtin_amdgcn_cvt_pk_f32_fp8(v.y, true), o2[3]);
;         o2[4] = __builtin_elementwise_fma(pp, __builtin_amdgcn_cvt_pk_f32_fp8(v.z, false), o2[4]); o2[5] = __builtin_elementwise_fma(pp, __builtin_amdgcn_cvt_pk_f32_fp8(v.z, true), o2[5]);
;         o2[6] = __builtin_elementwise_fma(pp, __builtin_amdgcn_cvt_pk_f32_fp8(v.w, false), o2[6]); o2[7] = __builtin_elementwise_fma(pp, __builtin_amdgcn_cvt_pk_f32_fp8(v.w, true), o2[7]);
;     }
	v_lshl_add_u32 v170, v170, 8, v138
	v_lshl_add_u32 v171, v171, 8, v138
	v_lshl_add_u32 v172, v172, 8, v138
	v_lshl_add_u32 v173, v173, 8, v138
	buffer_load_dwordx4 v[80:83], v170, s[16:19], s26 offen
	buffer_load_dwordx4 v[84:87], v171, s[16:19], s26 offen
	buffer_load_dwordx4 v[88:91], v172, s[16:19], s26 offen
	buffer_load_dwordx4 v[92:95], v173, s[16:19], s26 offen
	s_waitcnt vmcnt(29)
	v_cvt_pk_f32_fp8_e32 v[214:215], v104
	v_cvt_pk_f32_fp8_sdwa v[216:217], v104 src0_sel:WORD_1
	v_pk_fma_f32 v[198:199], v[176:177], v[214:215], v[198:199] op_sel_hi:[0,1,1]
	v_pk_fma_f32 v[200:201], v[176:177], v[216:217], v[200:201] op_sel_hi:[0,1,1]
	v_cvt_pk_f32_fp8_e32 v[218:219], v105
	v_cvt_pk_f32_fp8_sdwa v[220:221], v105 src0_sel:WORD_1
	v_pk_fma_f32 v[202:203], v[176:177], v[218:219], v[202:203] op_sel_hi:[0,1,1]
	v_pk_fma_f32 v[204:205], v[176:177], v[220:221], v[204:205] op_sel_hi:[0,1,1]
	v_cvt_pk_f32_fp8_e32 v[214:215], v106
	v_cvt_pk_f32_fp8_sdwa v[216:217], v106 src0_sel:WORD_1
	v_pk_fma_f32 v[206:207], v[176:177], v[214:215], v[206:207] op_sel_hi:[0,1,1]
	v_pk_fma_f32 v[208:209], v[176:177], v[216:217], v[208:209] op_sel_hi:[0,1,1]
	v_cvt_pk_f32_fp8_e32 v[218:219], v107
	v_cvt_pk_f32_fp8_sdwa v[220:221], v107 src0_sel:WORD_1
	v_pk_fma_f32 v[210:211], v[176:177], v[218:219], v[210:211] op_sel_hi:[0,1,1]
	v_pk_fma_f32 v[212:213], v[176:177], v[220:221], v[212:213] op_sel_hi:[0,1,1]
	s_waitcnt vmcnt(28)
	v_cvt_pk_f32_fp8_e32 v[214:215], v108
	v_cvt_pk_f32_fp8_sdwa v[216:217], v108 src0_sel:WORD_1
	v_pk_fma_f32 v[198:199], v[176:177], v[214:215], v[198:199] op_sel:[1,0,0]
	v_pk_fma_f32 v[200:201], v[176:177], v[216:217], v[200:201] op_sel:[1,0,0]
	v_cvt_pk_f32_fp8_e32 v[218:219], v109
	v_cvt_pk_f32_fp8_sdwa v[220:221], v109 src0_sel:WORD_1
	v_pk_fma_f32 v[202:203], v[176:177], v[218:219], v[202:203] op_sel:[1,0,0]
	v_pk_fma_f32 v[204:205], v[176:177], v[220:221], v[204:205] op_sel:[1,0,0]
	v_cvt_pk_f32_fp8_e32 v[214:215], v110
	v_cvt_pk_f32_fp8_sdwa v[216:217], v110 src0_sel:WORD_1
	v_pk_fma_f32 v[206:207], v[176:177], v[214:215], v[206:207] op_sel:[1,0,0]
	v_pk_fma_f32 v[208:209], v[176:177], v[216:217], v[208:209] op_sel:[1,0,0]
	v_cvt_pk_f32_fp8_e32 v[218:219], v111
	v_cvt_pk_f32_fp8_sdwa v[220:221], v111 src0_sel:WORD_1
	v_pk_fma_f32 v[210:211], v[176:177], v[218:219], v[210:211] op_sel:[1,0,0]
	v_pk_fma_f32 v[212:213], v[176:177], v[220:221], v[212:213] op_sel:[1,0,0]
	ds_read_b128 v[174:177], v139 offset:96
	s_waitcnt vmcnt(27)
	v_cvt_pk_f32_fp8_e32 v[214:215], v112
	v_cvt_pk_f32_fp8_sdwa v[216:217], v112 src0_sel:WORD_1
	v_pk_fma_f32 v[198:199], v[178:179], v[214:215], v[198:199] op_sel_hi:[0,1,1]
	v_pk_fma_f32 v[200:201], v[178:179], v[216:217], v[200:201] op_sel_hi:[0,1,1]
	v_cvt_pk_f32_fp8_e32 v[218:219], v113
	v_cvt_pk_f32_fp8_sdwa v[220:221], v113 src0_sel:WORD_1
	v_pk_fma_f32 v[202:203], v[178:179], v[218:219], v[202:203] op_sel_hi:[0,1,1]
	v_pk_fma_f32 v[204:205], v[178:179], v[220:221], v[204:205] op_sel_hi:[0,1,1]
	v_cvt_pk_f32_fp8_e32 v[214:215], v114
	v_cvt_pk_f32_fp8_sdwa v[216:217], v114 src0_sel:WORD_1
	v_pk_fma_f32 v[206:207], v[178:179], v[214:215], v[206:207] op_sel_hi:[0,1,1]
	v_pk_fma_f32 v[208:209], v[178:179], v[216:217], v[208:209] op_sel_hi:[0,1,1]
	v_cvt_pk_f32_fp8_e32 v[218:219], v115
	v_cvt_pk_f32_fp8_sdwa v[220:221], v115 src0_sel:WORD_1
	v_pk_fma_f32 v[210:211], v[178:179], v[218:219], v[210:211] op_sel_hi:[0,1,1]
	v_pk_fma_f32 v[212:213], v[178:179], v[220:221], v[212:213] op_sel_hi:[0,1,1]
	s_waitcnt vmcnt(26)
	v_cvt_pk_f32_fp8_e32 v[214:215], v116
	v_cvt_pk_f32_fp8_sdwa v[216:217], v116 src0_sel:WORD_1
	v_pk_fma_f32 v[198:199], v[178:179], v[214:215], v[198:199] op_sel:[1,0,0]
	v_pk_fma_f32 v[200:201], v[178:179], v[216:217], v[200:201] op_sel:[1,0,0]
	v_cvt_pk_f32_fp8_e32 v[218:219], v117
	v_cvt_pk_f32_fp8_sdwa v[220:221], v117 src0_sel:WORD_1
	v_pk_fma_f32 v[202:203], v[178:179], v[218:219], v[202:203] op_sel:[1,0,0]
	v_pk_fma_f32 v[204:205], v[178:179], v[220:221], v[204:205] op_sel:[1,0,0]
	v_cvt_pk_f32_fp8_e32 v[214:215], v118
	v_cvt_pk_f32_fp8_sdwa v[216:217], v118 src0_sel:WORD_1
	v_pk_fma_f32 v[206:207], v[178:179], v[214:215], v[206:207] op_sel:[1,0,0]
	v_pk_fma_f32 v[208:209], v[178:179], v[216:217], v[208:209] op_sel:[1,0,0]
	v_cvt_pk_f32_fp8_e32 v[218:219], v119
	v_cvt_pk_f32_fp8_sdwa v[220:221], v119 src0_sel:WORD_1
	v_pk_fma_f32 v[210:211], v[178:179], v[218:219], v[210:211] op_sel:[1,0,0]
	v_pk_fma_f32 v[212:213], v[178:179], v[220:221], v[212:213] op_sel:[1,0,0]
	s_waitcnt lgkmcnt(0)
	v_lshl_add_u32 v174, v174, 8, v138
	v_lshl_add_u32 v175, v175, 8, v138
	v_lshl_add_u32 v176, v176, 8, v138
	v_lshl_add_u32 v177, v177, 8, v138
	buffer_load_dwordx4 v[96:99], v174, s[16:19], s26 offen
	buffer_load_dwordx4 v[100:103], v175, s[16:19], s26 offen
	buffer_load_dwordx4 v[104:107], v176, s[16:19], s26 offen
	buffer_load_dwordx4 v[108:111], v177, s[16:19], s26 offen
	s_waitcnt vmcnt(29)
; __device__ __forceinline__ unsigned cvt_pk_bf16(float lo, float hi) { unsigned r; asm volatile("v_cvt_pk_bf16_f32 %0, %1, %2" : "=v"(r) : "v"(lo), "v"(hi)); return r; }
; #define LAS __attribute__((address_space(3)))
; __device__ __forceinline__ void kv8_pv(const u32x4 (&buf)[8], f32x2v (&o2)[8], const LAS float* srow, int b) {
;     const LAS f32x4* p4 = (const LAS f32x4*)(srow + b * 8);
;     const f32x4 p0 = p4[0], p1 = p4[1];
;     const float p[8] = {p0.x, p0.y, p0.z, p0.w, p1.x, p1.y, p1.z, p1.w};
; #pragma unroll
;     for (int u = 0; u < 8; ++u) {
;         const u32x4 v = buf[u]; const f32x2v pp = {p[u], p[u]};
;         o2[0] = __builtin_elementwise_fma(pp, __builtin_amdgcn_cvt_pk_f32_fp8(v.x, false), o2[0]); o2[1] = __builtin_elementwise_fma(pp, __builtin_amdgcn_cvt_pk_f32_fp8(v.x, true), o2[1]);
;         o2[2] = __builtin_elementwise_fma(pp, __builtin_amdgcn_cvt_pk_f32_fp8(v.y, false), o2[2]); o2[3] = __builtin_elementwise_fma(pp, __builtin_amdgcn_cvt_pk_f32_fp8(v.y, true), o2[3]);
;         o2[4] = __builtin_elementwise_fma(pp, __builtin_amdgcn_cvt_pk_f32_fp8(v.z, false), o2[4]); o2[5] = __builtin_elementwise_fma(pp, __builtin_amdgcn_cvt_pk_f32_fp8(v.z, true), o2[5]);
;         o2[6] = __builtin_elementwise_fma(pp, __builtin_amdgcn_cvt_pk_f32_fp8(v.w, false), o2[6]); o2[7] = __builtin_elementwise_fma(pp, __builtin_amdgcn_cvt_pk_f32_fp8(v.w, true), o2[7]);
;     }
; __device__ __forceinline__ void attn_query8(const unsigned char* __restrict__ KV8, const bf16_t* __restrict__ Z, const int* __restrict__ SEL, bf16_t* __restrict__ YMIX, int t, LAS float* sbuf  ) {
;     ...
;     for (int b = 0; b < nb; b += 3) {
;         kv8_issue(C, rs, lvo, 1024, iv, CLAMPB(b + 2));
;         kv8_pv(A, o, srow, b);
;         kv8_issue(A, rs, lvo, 1024, iv, CLAMPB(b + 3));
;         if (b + 1 < nb) kv8_pv(B, o, srow, b + 1);
;         kv8_issue(B, rs, lvo, 1024, iv, CLAMPB(b + 4));
;         if (b + 2 < nb) kv8_pv(C, o, srow, b + 2);
;     }
;     ...
;     u32x4 o0, o1;
;     o0.x = cvt_pk_bf16(o[0].x, o[0].y); o0.y = cvt_pk_bf16(o[1].x, o[1].y); o0.z = cvt_pk_bf16(o[2].x, o[2].y); o0.w = cvt_pk_bf16(o[3].x, o[3].y);
;     o1.x = cvt_pk_bf16(o[4].x, o[4].y); o1.y = cvt_pk_bf16(o[5].x, o[5].y); o1.z = cvt_pk_bf16(o[6].x, o[6].y); o1.w = cvt_pk_bf16(o[7].x, o[7].y);
;     u32x4* yp = (u32x4*)(YMIX + (size_t)t * D_ + 1024 + lane * 16);
;     yp[0] = o0; yp[1] = o1;
	v_cvt_pk_f32_fp8_e32 v[214:215], v120
	v_cvt_pk_f32_fp8_sdwa v[216:217], v120 src0_sel:WORD_1
	v_pk_fma_f32 v[198:199], v[180:181], v[214:215], v[198:199] op_sel_hi:[0,1,1]
	v_pk_fma_f32 v[200:201], v[180:181], v[216:217], v[200:201] op_sel_hi:[0,1,1]
	v_cvt_pk_f32_fp8_e32 v[218:219], v121
	v_cvt_pk_f32_fp8_sdwa v[220:221], v121 src0_sel:WORD_1
	v_pk_fma_f32 v[202:203], v[180:181], v[218:219], v[202:203] op_sel_hi:[0,1,1]
	v_pk_fma_f32 v[204:205], v[180:181], v[220:221], v[204:205] op_sel_hi:[0,1,1]
	v_cvt_pk_f32_fp8_e32 v[214:215], v122
	v_cvt_pk_f32_fp8_sdwa v[216:217], v122 src0_sel:WORD_1
	v_pk_fma_f32 v[206:207], v[180:181], v[214:215], v[206:207] op_sel_hi:[0,1,1]
	v_pk_fma_f32 v[208:209], v[180:181], v[216:217], v[208:209] op_sel_hi:[0,1,1]
	v_cvt_pk_f32_fp8_e32 v[218:219], v123
	v_cvt_pk_f32_fp8_sdwa v[220:221], v123 src0_sel:WORD_1
	v_pk_fma_f32 v[210:211], v[180:181], v[218:219], v[210:211] op_sel_hi:[0,1,1]
	v_pk_fma_f32 v[212:213], v[180:181], v[220:221], v[212:213] op_sel_hi:[0,1,1]
	s_waitcnt vmcnt(28)
	v_cvt_pk_f32_fp8_e32 v[214:215], v124
	v_cvt_pk_f32_fp8_sdwa v[216:217], v124 src0_sel:WORD_1
	v_pk_fma_f32 v[198:199], v[180:181], v[214:215], v[198:199] op_sel:[1,0,0]
	v_pk_fma_f32 v[200:201], v[180:181], v[216:217], v[200:201] op_sel:[1,0,0]
	v_cvt_pk_f32_fp8_e32 v[218:219], v125
	v_cvt_pk_f32_fp8_sdwa v[220:221], v125 src0_sel:WORD_1
	v_pk_fma_f32 v[202:203], v[180:181], v[218:219], v[202:203] op_sel:[1,0,0]
	v_pk_fma_f32 v[204:205], v[180:181], v[220:221], v[204:205] op_sel:[1,0,0]
	v_cvt_pk_f32_fp8_e32 v[214:215], v126
	v_cvt_pk_f32_fp8_sdwa v[216:217], v126 src0_sel:WORD_1
	v_pk_fma_f32 v[206:207], v[180:181], v[214:215], v[206:207] op_sel:[1,0,0]
	v_pk_fma_f32 v[208:209], v[180:181], v[216:217], v[208:209] op_sel:[1,0,0]
	v_cvt_pk_f32_fp8_e32 v[218:219], v127
	v_cvt_pk_f32_fp8_sdwa v[220:221], v127 src0_sel:WORD_1
	v_pk_fma_f32 v[210:211], v[180:181], v[218:219], v[210:211] op_sel:[1,0,0]
	v_pk_fma_f32 v[212:213], v[180:181], v[220:221], v[212:213] op_sel:[1,0,0]
	ds_read_b128 v[178:181], v139 offset:112
	v_add_f32_dpp v198, v198, v198 row_ror:8 row_mask:0xf bank_mask:0x3
	v_add_f32_dpp v199, v199, v199 row_ror:8 row_mask:0xf bank_mask:0x3
	v_add_f32_dpp v200, v200, v200 row_ror:8 row_mask:0xf bank_mask:0x3
	v_add_f32_dpp v201, v201, v201 row_ror:8 row_mask:0xf bank_mask:0x3
	v_add_f32_dpp v202, v202, v202 row_ror:8 row_mask:0xf bank_mask:0x3
	v_add_f32_dpp v203, v203, v203 row_ror:8 row_mask:0xf bank_mask:0x3
	v_add_f32_dpp v204, v204, v204 row_ror:8 row_mask:0xf bank_mask:0x3
	v_add_f32_dpp v205, v205, v205 row_ror:8 row_mask:0xf bank_mask:0x3
	v_add_f32_dpp v206, v206, v206 row_ror:8 row_mask:0xf bank_mask:0xc
	v_add_f32_dpp v207, v207, v207 row_ror:8 row_mask:0xf bank_mask:0xc
	v_add_f32_dpp v208, v208, v208 row_ror:8 row_mask:0xf bank_mask:0xc
	v_add_f32_dpp v209, v209, v209 row_ror:8 row_mask:0xf bank_mask:0xc
	v_add_f32_dpp v210, v210, v210 row_ror:8 row_mask:0xf bank_mask:0xc
	v_add_f32_dpp v211, v211, v211 row_ror:8 row_mask:0xf bank_mask:0xc
	v_add_f32_dpp v212, v212, v212 row_ror:8 row_mask:0xf bank_mask:0xc
	v_add_f32_dpp v213, v213, v213 row_ror:8 row_mask:0xf bank_mask:0xc
	v_mov_b32_dpp v198, v206 quad_perm:[0,1,2,3] row_mask:0xf bank_mask:0xc
	v_mov_b32_dpp v199, v207 quad_perm:[0,1,2,3] row_mask:0xf bank_mask:0xc
	v_mov_b32_dpp v200, v208 quad_perm:[0,1,2,3] row_mask:0xf bank_mask:0xc
	v_mov_b32_dpp v201, v209 quad_perm:[0,1,2,3] row_mask:0xf bank_mask:0xc
	v_mov_b32_dpp v202, v210 quad_perm:[0,1,2,3] row_mask:0xf bank_mask:0xc
	v_mov_b32_dpp v203, v211 quad_perm:[0,1,2,3] row_mask:0xf bank_mask:0xc
	v_mov_b32_dpp v204, v212 quad_perm:[0,1,2,3] row_mask:0xf bank_mask:0xc
	v_mov_b32_dpp v205, v213 quad_perm:[0,1,2,3] row_mask:0xf bank_mask:0xc
	s_waitcnt lgkmcnt(0)
	v_lshl_add_u32 v178, v178, 8, v138
	v_lshl_add_u32 v179, v179, 8, v138
	v_lshl_add_u32 v180, v180, 8, v138
	v_lshl_add_u32 v181, v181, 8, v138
	buffer_load_dwordx4 v[112:115], v178, s[16:19], s26 offen
	buffer_load_dwordx4 v[116:119], v179, s[16:19], s26 offen
	buffer_load_dwordx4 v[120:123], v180, s[16:19], s26 offen
	buffer_load_dwordx4 v[124:127], v181, s[16:19], s26 offen
	s_nop 1
	v_permlane16_swap_b32_e32 v198, v202
	v_add_f32_e32 v198, v198, v202
	v_permlane16_swap_b32_e32 v199, v203
	v_add_f32_e32 v199, v199, v203
	v_permlane16_swap_b32_e32 v200, v204
	v_add_f32_e32 v200, v200, v204
	v_permlane16_swap_b32_e32 v201, v205
	v_add_f32_e32 v201, v201, v205
	s_nop 0
	v_permlane32_swap_b32_e32 v198, v200
	v_add_f32_e32 v198, v198, v200
	v_permlane32_swap_b32_e32 v199, v201
	v_add_f32_e32 v199, v199, v201
	s_ashr_i32 s81, s80, 31
	s_lshl_b64 s[10:11], s[80:81], 12
	s_add_u32 s10, s14, s10
	s_addc_u32 s11, s15, s11
	v_mul_f32_e32 v198, v198, v149
	v_mul_f32_e32 v199, v199, v149
	v_cvt_pk_bf16_f32 v214, v198, v199
	global_store_dword v238, v214, s[10:11] offset:2048
	s_addk_i32 s80, 0x100
	s_cmpk_gt_i32 s80, 0x3fff
	s_cbranch_scc0 .Latt_unit
	s_waitcnt vmcnt(0)
